# combination plus: layer 0's W_glu items converted in the prologue and its W_out items by the idle workgroups of the GLU GEMM instead of the first scan pass
# speedup vs baseline: 1.0197x; 1.0009x over previous
.LBB0_119:
	v_readlane_b32 s0, v247, 9
	v_readlane_b32 s1, v247, 10
	s_andn2_b64 vcc, exec, s[0:1]
	s_cbranch_vccnz .Lmod_host
	s_cmpk_lt_i32 s14, 0xc1
	s_cselect_b64 s[4:5], -1, 0
	s_cmpk_gt_i32 s2, 0xbf
	s_cselect_b64 s[0:1], -1, 0
	s_or_b64 s[0:1], s[4:5], s[0:1]
	s_andn2_b64 vcc, exec, s[0:1]
	s_cbranch_vccnz .LBB0_140
	s_sub_i32 s4, s2, 0xc0
	s_lshl_b32 s4, s4, 3
	s_add_i32 s4, s4, s43
	s_movk_i32 s1, 0x200
	s_movk_i32 s25, 4608
	s_movk_i32 s39, 8156
	s_branch .Lconv_entry
	s_lshl_b32 s1, s14, 3
	s_add_i32 s3, s1, 0xfffffa00
	s_and_b64 s[4:5], s[4:5], exec
	s_cselect_b32 s1, s1, s3
	s_lshl_b32 s3, s43, 14
	s_add_i32 s4, s3, 0
	s_add_u32 s3, s56, 0x9c00000
	s_addc_u32 s12, s57, 0
	s_add_u32 s13, s56, 0x4400000
	v_lshrrev_b32_e32 v1, 5, v168
	v_and_b32_e32 v0, 31, v241
	s_addc_u32 s15, s57, 0
	v_lshlrev_b32_e32 v2, 2, v0
	v_mul_u32_u24_e32 v3, 0x84, v1
	s_add_u32 s18, s56, 0x3400000
	v_add3_u32 v3, s4, v2, v3
	v_lshlrev_b32_e32 v2, 3, v168
	s_addc_u32 s19, s57, 0
	v_lshrrev_b32_e32 v5, 3, v168
	v_and_b32_e32 v2, 56, v2
	s_add_u32 s25, s56, 0x1000000
	v_mul_u32_u24_e32 v6, 0x84, v2
	v_lshlrev_b32_e32 v7, 2, v5
	s_addc_u32 s36, s57, 0
	s_add_i32 s37, s0, 0x1a00
	v_add3_u32 v10, s4, v6, v7
	v_or_b32_e32 v11, 8, v5
	v_or_b32_e32 v12, 16, v5
	v_or_b32_e32 v13, 24, v5
	s_lshl_b32 s38, s37, 1
	s_lshl_b32 s39, s1, 1
	s_lshl_b32 s40, s0, 5
	s_lshl_b32 s41, s1, 5
	s_branch .LBB0_124

.LBB0_196:
	s_cmpk_lt_i32 s2, 0x80
	s_cbranch_scc1 .LBB0_219
	s_sub_i32 s4, s2, 0x80
	s_lshl_b32 s4, s4, 3
	s_add_i32 s4, s4, s43
	s_movk_i32 s1, 0x400
	s_and_b64 s[6:7], s[62:63], exec
	s_mov_b32 s25, 8156
	s_mov_b32 s39, 17920
	s_cbranch_scc0 .Lconv_entry
	s_mov_b32 s25, 32208
	s_mov_b32 s39, 41472

.LBB0_219:
	s_cmp_eq_u32 s35, 4
	s_cbranch_scc0 .Lconv_ret_n4
	s_mov_b64 s[8:9], 0
	s_branch .LBB0_140

.LBB0_402:
	v_readlane_b32 s0, v247, 9
	v_readlane_b32 s1, v247, 10
	v_readlane_b32 s72, v247, 5
	v_readlane_b32 s68, v247, 7
	s_and_b64 vcc, exec, s[0:1]
	v_readlane_b32 s73, v247, 6
	v_readlane_b32 s69, v247, 8
	s_cbranch_vccz .LBB0_441
	s_branch .LBB0_441
	s_add_i32 s1, s6, 0x1000
	s_add_u32 s3, s56, 0x9c00000
	s_addc_u32 s5, s57, 0
	s_add_u32 s7, s56, 0x4400000
	s_addc_u32 s12, s57, 0
	s_add_u32 s13, s56, 0x3400000
	s_addc_u32 s15, s57, 0
	s_add_u32 s18, s56, 0x3000000
	v_lshrrev_b32_e32 v1, 5, v168
	v_and_b32_e32 v0, 31, v241
	s_addc_u32 s19, s57, 0
	v_lshlrev_b32_e32 v2, 2, v0
	v_mul_u32_u24_e32 v3, 0x84, v1
	s_add_u32 s25, s56, 0x1000000
	v_add3_u32 v3, s78, v2, v3
	v_lshlrev_b32_e32 v2, 3, v168
	s_addc_u32 s36, s57, 0
	v_lshrrev_b32_e32 v5, 3, v168
	v_and_b32_e32 v2, 56, v2
	s_lshl_b32 s0, s6, 5
	v_mul_u32_u24_e32 v6, 0x84, v2
	v_lshlrev_b32_e32 v7, 2, v5
	s_add_i32 s37, s0, 0x20000
	s_lshl_b32 s0, s6, 1
	v_add3_u32 v10, s78, v6, v7
	v_or_b32_e32 v11, 8, v5
	v_or_b32_e32 v12, 16, v5
	v_or_b32_e32 v13, 24, v5
	s_lshl_b32 s38, s4, 5
	s_add_i32 s39, s0, 0x2000
	s_lshl_b32 s40, s4, 1
	s_branch .LBB0_406

.LBB0_469:
	s_or_b64 exec, exec, s[8:9]
	s_lshl_b32 s0, s43, 14
	s_add_i32 s34, s0, 0
	s_lshl_b32 s0, s2, 3
	s_add_i32 s12, s43, s0
	s_lshl_b32 s13, s14, 3
	s_cmpk_gt_i32 s14, 0xc0
	s_mov_b64 s[4:5], -1
	s_cbranch_scc0 .LBB0_499
	v_cvt_f32_u32_e32 v0, s13
	s_sub_i32 s0, 0, s13
	v_rcp_iflag_f32_e32 v0, v0
	s_nop 0
	v_mul_f32_e32 v0, 0x4f7ffffe, v0
	v_cvt_u32_f32_e32 v0, v0
	s_nop 0
	v_readfirstlane_b32 s1, v0
	s_mul_i32 s0, s0, s1
	s_mul_hi_u32 s0, s1, s0
	s_add_i32 s1, s1, s0
	s_mul_hi_u32 s0, s1, 0x5200
	s_mul_i32 s1, s0, s13
	s_sub_i32 s1, 0x5200, s1
	s_add_i32 s3, s0, 1
	s_sub_i32 s4, s1, s13
	s_cmp_ge_u32 s1, s13
	s_cselect_b32 s0, s3, s0
	s_cselect_b32 s1, s4, s1
	s_add_i32 s3, s0, 1
	s_cmp_ge_u32 s1, s13
	s_cselect_b32 s0, s3, s0
	v_sub_u32_e64 v0, s0, 16 clamp
	s_cmpk_gt_i32 s12, 0x3ff
	v_readfirstlane_b32 s1, v0
	s_mov_b64 s[4:5], -1
	s_cbranch_scc1 .LBB0_473
	s_andn2_b64 vcc, exec, s[4:5]
	s_cbranch_vccz .LBB0_474

.LBB0_473:
	s_add_i32 s0, s13, 0xfffffc00
	s_abs_i32 s3, s0
	v_cvt_f32_u32_e32 v0, s3
	s_mul_i32 s4, s1, 0x400
	s_waitcnt lgkmcnt(0)
	s_sub_i32 s6, 0, s3
	s_sub_i32 s5, s13, s4
	v_rcp_iflag_f32_e32 v0, v0
	s_addk_i32 s5, 0xdff
	s_xor_b32 s0, s5, s0
	s_abs_i32 s5, s5
	v_mul_f32_e32 v0, 0x4f7ffffe, v0
	v_cvt_u32_f32_e32 v0, v0
	s_ashr_i32 s0, s0, 31
	v_readfirstlane_b32 s7, v0
	s_mul_i32 s6, s6, s7
	s_mul_hi_u32 s6, s7, s6
	s_add_i32 s7, s7, s6
	s_mul_hi_u32 s6, s5, s7
	s_mul_i32 s7, s6, s3
	s_sub_i32 s5, s5, s7
	s_add_i32 s8, s6, 1
	s_sub_i32 s7, s5, s3
	s_cmp_ge_u32 s5, s3
	s_cselect_b32 s6, s8, s6
	s_cselect_b32 s5, s7, s5
	s_add_i32 s7, s6, 1
	s_cmp_ge_u32 s5, s3
	s_cselect_b32 s3, s7, s6
	s_xor_b32 s3, s3, s0
	s_sub_i32 s0, s3, s0
	s_add_i32 s3, s12, 0xfffffc00
	s_mul_i32 s3, s0, s3
	s_add_i32 s3, s3, s4
	s_add_i32 s0, s3, s0
	s_min_i32 s8, s0, 0x1200
	s_cbranch_execnz .LBB0_472
